# v11 plus: DeltaNet chunk-local forward substitution (I+L)X=RHS rewritten by hand in f32: all 8 waves (16 columns each, 4 lane groups split off-diagonal rows, diagonal 16x16 blocks solved per lane) ins
# speedup vs baseline: 1.0130x; 1.0130x over previous
.LBB0_628:
	s_or_b64 exec, exec, s[2:3]
	s_movk_i32 s2, 0x80
	v_cmp_gt_i32_e64 s[4:5], s2, v16
	s_waitcnt lgkmcnt(0)
	s_barrier
	s_mov_b64 s[6:7], exec
	v_readfirstlane_b32 s2, v160
	v_and_b32_e32 v13, 15, v160
	v_bfe_u32 v14, v160, 4, 2
	s_lshr_b32 s2, s2, 6
	s_and_b32 s4, s2, 3
	s_lshl_b32 s4, s4, 6
	s_cmp_lt_u32 s2, 4
	s_mov_b32 s5, 0x4100
	s_cselect_b32 s5, 0x8200, s5
	s_mov_b32 s2, 0x10900
	s_cselect_b32 s2, 0x10800, s2
	s_add_u32 s4, s4, s5
	v_lshl_add_u32 v9, v13, 2, v195
	v_add_u32_e32 v9, s4, v9
	v_mul_u32_u24_e32 v15, 0x410, v14
	v_add_u32_e32 v8, v9, v15
	v_lshl_add_u32 v10, v14, 4, v195
	v_add_u32_e32 v10, s2, v10
	v_add_u32_e32 v12, 0xc300, v195
	v_mul_u32_u24_e32 v15, 0x440, v14
	v_add_u32_e32 v11, v12, v15
	ds_read_b32 v21, v8 offset:0
	ds_read_b32 v22, v8 offset:260
	ds_read_b32 v23, v8 offset:520
	ds_read_b32 v24, v8 offset:780
	ds_read_b32 v27, v10 offset:0
	ds_read_b32 v28, v10 offset:4
	ds_read_b32 v29, v10 offset:8
	ds_read_b32 v30, v10 offset:12
	s_waitcnt lgkmcnt(7)
	s_waitcnt lgkmcnt(3)
	v_mul_f32_e32 v13, v21, v27
	s_waitcnt lgkmcnt(2)
	v_mul_f32_e32 v14, v22, v28
	s_waitcnt lgkmcnt(1)
	v_mul_f32_e32 v15, v23, v29
	s_waitcnt lgkmcnt(0)
	v_mul_f32_e32 v20, v24, v30
	ds_write_b32 v8, v13 offset:0
	ds_write_b32 v8, v14 offset:260
	ds_write_b32 v8, v15 offset:520
	ds_write_b32 v8, v20 offset:780
	ds_read_b32 v31, v9 offset:0
	ds_read_b32 v32, v9 offset:260
	ds_read_b32 v33, v9 offset:520
	ds_read_b32 v34, v9 offset:780
	ds_read_b32 v35, v9 offset:1040
	ds_read_b32 v36, v9 offset:1300
	ds_read_b32 v37, v9 offset:1560
	ds_read_b32 v38, v9 offset:1820
	ds_read_b32 v39, v9 offset:2080
	ds_read_b32 v40, v9 offset:2340
	ds_read_b32 v41, v9 offset:2600
	s_waitcnt lgkmcnt(14)
	ds_read_b32 v42, v9 offset:2860
	s_waitcnt lgkmcnt(14)
	ds_read_b32 v43, v9 offset:3120
	s_waitcnt lgkmcnt(14)
	ds_read_b32 v44, v9 offset:3380
	s_waitcnt lgkmcnt(14)
	ds_read_b32 v45, v9 offset:3640
	s_waitcnt lgkmcnt(14)
	ds_read_b32 v46, v9 offset:3900
	s_waitcnt lgkmcnt(12)
	ds_read_b128 v[214:217], v12 offset:272
	ds_read_b128 v[230:233], v12 offset:544
	v_mov_b32_e32 v64, v31
	ds_read_b128 v[198:201], v12 offset:816
	s_waitcnt lgkmcnt(2)
	v_fma_f32 v65, -v214, v64, v32
	ds_read_b128 v[214:217], v12 offset:1088
	s_waitcnt lgkmcnt(2)
	v_fma_f32 v66, -v230, v64, v33
	v_fma_f32 v66, -v231, v65, v66
	ds_read_b128 v[230:233], v12 offset:1360
	ds_read_b128 v[234:237], v12 offset:1376
	s_waitcnt lgkmcnt(3)
	v_fma_f32 v67, -v198, v64, v34
	v_fma_f32 v67, -v199, v65, v67
	v_fma_f32 v67, -v200, v66, v67
	ds_read_b128 v[198:201], v12 offset:1632
	ds_read_b128 v[202:205], v12 offset:1648
	s_waitcnt lgkmcnt(4)
	v_fma_f32 v68, -v214, v64, v35
	v_fma_f32 v68, -v215, v65, v68
	v_fma_f32 v68, -v216, v66, v68
	v_fma_f32 v68, -v217, v67, v68
	ds_read_b128 v[214:217], v12 offset:1904
	ds_read_b128 v[218:221], v12 offset:1920
	s_waitcnt lgkmcnt(5)
	v_fma_f32 v69, -v230, v64, v36
	v_fma_f32 v69, -v231, v65, v69
	v_fma_f32 v69, -v232, v66, v69
	v_fma_f32 v69, -v233, v67, v69
	s_waitcnt lgkmcnt(4)
	v_fma_f32 v69, -v234, v68, v69
	ds_read_b128 v[230:233], v12 offset:2176
	ds_read_b128 v[234:237], v12 offset:2192
	s_waitcnt lgkmcnt(5)
	v_fma_f32 v70, -v198, v64, v37
	v_fma_f32 v70, -v199, v65, v70
	v_fma_f32 v70, -v200, v66, v70
	v_fma_f32 v70, -v201, v67, v70
	s_waitcnt lgkmcnt(4)
	v_fma_f32 v70, -v202, v68, v70
	v_fma_f32 v70, -v203, v69, v70
	ds_read_b128 v[198:201], v12 offset:2448
	ds_read_b128 v[202:205], v12 offset:2464
	ds_read_b128 v[206:209], v12 offset:2480
	s_waitcnt lgkmcnt(6)
	v_fma_f32 v71, -v214, v64, v38
	v_fma_f32 v71, -v215, v65, v71
	v_fma_f32 v71, -v216, v66, v71
	v_fma_f32 v71, -v217, v67, v71
	s_waitcnt lgkmcnt(5)
	v_fma_f32 v71, -v218, v68, v71
	v_fma_f32 v71, -v219, v69, v71
	v_fma_f32 v71, -v220, v70, v71
	ds_read_b128 v[214:217], v12 offset:2720
	ds_read_b128 v[218:221], v12 offset:2736
	ds_read_b128 v[222:225], v12 offset:2752
	s_waitcnt lgkmcnt(7)
	v_fma_f32 v72, -v230, v64, v39
	v_fma_f32 v72, -v231, v65, v72
	v_fma_f32 v72, -v232, v66, v72
	v_fma_f32 v72, -v233, v67, v72
	s_waitcnt lgkmcnt(6)
	v_fma_f32 v72, -v234, v68, v72
	v_fma_f32 v72, -v235, v69, v72
	v_fma_f32 v72, -v236, v70, v72
	v_fma_f32 v72, -v237, v71, v72
	ds_read_b128 v[230:233], v12 offset:2992
	ds_read_b128 v[234:237], v12 offset:3008
	ds_read_b128 v[156:159], v12 offset:3024
	s_waitcnt lgkmcnt(8)
	v_fma_f32 v73, -v198, v64, v40
	v_fma_f32 v73, -v199, v65, v73
	v_fma_f32 v73, -v200, v66, v73
	v_fma_f32 v73, -v201, v67, v73
	s_waitcnt lgkmcnt(7)
	v_fma_f32 v73, -v202, v68, v73
	v_fma_f32 v73, -v203, v69, v73
	v_fma_f32 v73, -v204, v70, v73
	v_fma_f32 v73, -v205, v71, v73
	s_waitcnt lgkmcnt(6)
	v_fma_f32 v73, -v206, v72, v73
	ds_read_b128 v[198:201], v12 offset:3264
	ds_read_b128 v[202:205], v12 offset:3280
	ds_read_b128 v[206:209], v12 offset:3296
	s_waitcnt lgkmcnt(8)
	v_fma_f32 v74, -v214, v64, v41
	v_fma_f32 v74, -v215, v65, v74
	v_fma_f32 v74, -v216, v66, v74
	v_fma_f32 v74, -v217, v67, v74
	s_waitcnt lgkmcnt(7)
	v_fma_f32 v74, -v218, v68, v74
	v_fma_f32 v74, -v219, v69, v74
	v_fma_f32 v74, -v220, v70, v74
	v_fma_f32 v74, -v221, v71, v74
	s_waitcnt lgkmcnt(6)
	v_fma_f32 v74, -v222, v72, v74
	v_fma_f32 v74, -v223, v73, v74
	ds_read_b128 v[214:217], v12 offset:3536
	ds_read_b128 v[218:221], v12 offset:3552
	ds_read_b128 v[222:225], v12 offset:3568
	ds_read_b128 v[226:229], v12 offset:3584
	s_waitcnt lgkmcnt(9)
	v_fma_f32 v75, -v230, v64, v42
	v_fma_f32 v75, -v231, v65, v75
	v_fma_f32 v75, -v232, v66, v75
	v_fma_f32 v75, -v233, v67, v75
	s_waitcnt lgkmcnt(8)
	v_fma_f32 v75, -v234, v68, v75
	v_fma_f32 v75, -v235, v69, v75
	v_fma_f32 v75, -v236, v70, v75
	v_fma_f32 v75, -v237, v71, v75
	s_waitcnt lgkmcnt(7)
	v_fma_f32 v75, -v156, v72, v75
	v_fma_f32 v75, -v157, v73, v75
	v_fma_f32 v75, -v158, v74, v75
	ds_read_b128 v[230:233], v12 offset:3808
	ds_read_b128 v[234:237], v12 offset:3824
	ds_read_b128 v[156:159], v12 offset:3840
	ds_read_b128 v[164:167], v12 offset:3856
	s_waitcnt lgkmcnt(10)
	v_fma_f32 v76, -v198, v64, v43
	v_fma_f32 v76, -v199, v65, v76
	v_fma_f32 v76, -v200, v66, v76
	v_fma_f32 v76, -v201, v67, v76
	s_waitcnt lgkmcnt(9)
	v_fma_f32 v76, -v202, v68, v76
	v_fma_f32 v76, -v203, v69, v76
	v_fma_f32 v76, -v204, v70, v76
	v_fma_f32 v76, -v205, v71, v76
	s_waitcnt lgkmcnt(8)
	v_fma_f32 v76, -v206, v72, v76
	v_fma_f32 v76, -v207, v73, v76
	v_fma_f32 v76, -v208, v74, v76
	v_fma_f32 v76, -v209, v75, v76
	ds_read_b128 v[198:201], v12 offset:4080
	ds_read_b128 v[202:205], v12 offset:4096
	ds_read_b128 v[206:209], v12 offset:4112
	ds_read_b128 v[210:213], v12 offset:4128
	s_waitcnt lgkmcnt(11)
	v_fma_f32 v77, -v214, v64, v44
	v_fma_f32 v77, -v215, v65, v77
	v_fma_f32 v77, -v216, v66, v77
	v_fma_f32 v77, -v217, v67, v77
	s_waitcnt lgkmcnt(10)
	v_fma_f32 v77, -v218, v68, v77
	v_fma_f32 v77, -v219, v69, v77
	v_fma_f32 v77, -v220, v70, v77
	v_fma_f32 v77, -v221, v71, v77
	s_waitcnt lgkmcnt(9)
	v_fma_f32 v77, -v222, v72, v77
	v_fma_f32 v77, -v223, v73, v77
	v_fma_f32 v77, -v224, v74, v77
	v_fma_f32 v77, -v225, v75, v77
	s_waitcnt lgkmcnt(8)
	v_fma_f32 v77, -v226, v76, v77
	s_waitcnt lgkmcnt(7)
	v_fma_f32 v78, -v230, v64, v45
	v_fma_f32 v78, -v231, v65, v78
	v_fma_f32 v78, -v232, v66, v78
	v_fma_f32 v78, -v233, v67, v78
	s_waitcnt lgkmcnt(6)
	v_fma_f32 v78, -v234, v68, v78
	v_fma_f32 v78, -v235, v69, v78
	v_fma_f32 v78, -v236, v70, v78
	v_fma_f32 v78, -v237, v71, v78
	s_waitcnt lgkmcnt(5)
	v_fma_f32 v78, -v156, v72, v78
	v_fma_f32 v78, -v157, v73, v78
	v_fma_f32 v78, -v158, v74, v78
	v_fma_f32 v78, -v159, v75, v78
	s_waitcnt lgkmcnt(4)
	v_fma_f32 v78, -v164, v76, v78
	v_fma_f32 v78, -v165, v77, v78
	s_waitcnt lgkmcnt(3)
	v_fma_f32 v79, -v198, v64, v46
	v_fma_f32 v79, -v199, v65, v79
	v_fma_f32 v79, -v200, v66, v79
	v_fma_f32 v79, -v201, v67, v79
	s_waitcnt lgkmcnt(2)
	v_fma_f32 v79, -v202, v68, v79
	v_fma_f32 v79, -v203, v69, v79
	v_fma_f32 v79, -v204, v70, v79
	v_fma_f32 v79, -v205, v71, v79
	s_waitcnt lgkmcnt(1)
	v_fma_f32 v79, -v206, v72, v79
	v_fma_f32 v79, -v207, v73, v79
	v_fma_f32 v79, -v208, v74, v79
	v_fma_f32 v79, -v209, v75, v79
	s_waitcnt lgkmcnt(0)
	v_fma_f32 v79, -v210, v76, v79
	v_fma_f32 v79, -v211, v77, v79
	v_fma_f32 v79, -v212, v78, v79
	s_mov_b64 exec, 0xffff
	ds_write_b32 v9, v64 offset:0
	ds_write_b32 v9, v65 offset:260
	ds_write_b32 v9, v66 offset:520
	ds_write_b32 v9, v67 offset:780
	ds_write_b32 v9, v68 offset:1040
	ds_write_b32 v9, v69 offset:1300
	ds_write_b32 v9, v70 offset:1560
	ds_write_b32 v9, v71 offset:1820
	ds_write_b32 v9, v72 offset:2080
	ds_write_b32 v9, v73 offset:2340
	ds_write_b32 v9, v74 offset:2600
	ds_write_b32 v9, v75 offset:2860
	ds_write_b32 v9, v76 offset:3120
	ds_write_b32 v9, v77 offset:3380
	ds_write_b32 v9, v78 offset:3640
	s_waitcnt lgkmcnt(14)
	ds_write_b32 v9, v79 offset:3900
	s_mov_b64 exec, s[6:7]
	s_waitcnt lgkmcnt(0)
	ds_read_b32 v21, v8 offset:4160
	ds_read_b32 v22, v8 offset:4420
	ds_read_b32 v23, v8 offset:4680
	ds_read_b32 v24, v8 offset:4940
	ds_read_b32 v27, v10 offset:64
	ds_read_b32 v28, v10 offset:68
	ds_read_b32 v29, v10 offset:72
	ds_read_b32 v30, v10 offset:76
	ds_read_b128 v[124:127], v11 offset:4352
	ds_read_b128 v[128:131], v11 offset:4624
	ds_read_b128 v[132:135], v11 offset:4896
	ds_read_b128 v[136:139], v11 offset:5168
	ds_read_b128 v[140:143], v11 offset:4368
	ds_read_b128 v[144:147], v11 offset:4640
	ds_read_b128 v[148:151], v11 offset:4912
	s_waitcnt lgkmcnt(14)
	s_waitcnt lgkmcnt(10)
	v_mul_f32_e32 v13, v21, v27
	s_waitcnt lgkmcnt(9)
	v_mul_f32_e32 v14, v22, v28
	s_waitcnt lgkmcnt(8)
	v_mul_f32_e32 v15, v23, v29
	s_waitcnt lgkmcnt(7)
	v_mul_f32_e32 v20, v24, v30
	ds_read_b128 v[152:155], v11 offset:5184
	s_waitcnt lgkmcnt(7)
	v_fma_f32 v13, -v124, v64, v13
	v_fma_f32 v13, -v125, v65, v13
	v_fma_f32 v13, -v126, v66, v13
	v_fma_f32 v13, -v127, v67, v13
	ds_read_b128 v[124:127], v11 offset:4384
	s_waitcnt lgkmcnt(7)
	v_fma_f32 v14, -v128, v64, v14
	v_fma_f32 v14, -v129, v65, v14
	v_fma_f32 v14, -v130, v66, v14
	v_fma_f32 v14, -v131, v67, v14
	ds_read_b128 v[128:131], v11 offset:4656
	s_waitcnt lgkmcnt(7)
	v_fma_f32 v15, -v132, v64, v15
	v_fma_f32 v15, -v133, v65, v15
	v_fma_f32 v15, -v134, v66, v15
	v_fma_f32 v15, -v135, v67, v15
	ds_read_b128 v[132:135], v11 offset:4928
	s_waitcnt lgkmcnt(7)
	v_fma_f32 v20, -v136, v64, v20
	v_fma_f32 v20, -v137, v65, v20
	v_fma_f32 v20, -v138, v66, v20
	v_fma_f32 v20, -v139, v67, v20
	ds_read_b128 v[136:139], v11 offset:5200
	s_waitcnt lgkmcnt(7)
	v_fma_f32 v13, -v140, v68, v13
	v_fma_f32 v13, -v141, v69, v13
	v_fma_f32 v13, -v142, v70, v13
	v_fma_f32 v13, -v143, v71, v13
	ds_read_b128 v[140:143], v11 offset:4400
	s_waitcnt lgkmcnt(7)
	v_fma_f32 v14, -v144, v68, v14
	v_fma_f32 v14, -v145, v69, v14
	v_fma_f32 v14, -v146, v70, v14
	v_fma_f32 v14, -v147, v71, v14
	ds_read_b128 v[144:147], v11 offset:4672
	s_waitcnt lgkmcnt(7)
	v_fma_f32 v15, -v148, v68, v15
	v_fma_f32 v15, -v149, v69, v15
	v_fma_f32 v15, -v150, v70, v15
	v_fma_f32 v15, -v151, v71, v15
	ds_read_b128 v[148:151], v11 offset:4944
	s_waitcnt lgkmcnt(7)
	v_fma_f32 v20, -v152, v68, v20
	v_fma_f32 v20, -v153, v69, v20
	v_fma_f32 v20, -v154, v70, v20
	v_fma_f32 v20, -v155, v71, v20
	ds_read_b128 v[152:155], v11 offset:5216
	s_waitcnt lgkmcnt(7)
	v_fma_f32 v13, -v124, v72, v13
	v_fma_f32 v13, -v125, v73, v13
	v_fma_f32 v13, -v126, v74, v13
	v_fma_f32 v13, -v127, v75, v13
	s_waitcnt lgkmcnt(6)
	v_fma_f32 v14, -v128, v72, v14
	v_fma_f32 v14, -v129, v73, v14
	v_fma_f32 v14, -v130, v74, v14
	v_fma_f32 v14, -v131, v75, v14
	s_waitcnt lgkmcnt(5)
	v_fma_f32 v15, -v132, v72, v15
	v_fma_f32 v15, -v133, v73, v15
	v_fma_f32 v15, -v134, v74, v15
	v_fma_f32 v15, -v135, v75, v15
	s_waitcnt lgkmcnt(4)
	v_fma_f32 v20, -v136, v72, v20
	v_fma_f32 v20, -v137, v73, v20
	v_fma_f32 v20, -v138, v74, v20
	v_fma_f32 v20, -v139, v75, v20
	s_waitcnt lgkmcnt(3)
	v_fma_f32 v13, -v140, v76, v13
	v_fma_f32 v13, -v141, v77, v13
	v_fma_f32 v13, -v142, v78, v13
	v_fma_f32 v13, -v143, v79, v13
	s_waitcnt lgkmcnt(2)
	v_fma_f32 v14, -v144, v76, v14
	v_fma_f32 v14, -v145, v77, v14
	v_fma_f32 v14, -v146, v78, v14
	v_fma_f32 v14, -v147, v79, v14
	s_waitcnt lgkmcnt(1)
	v_fma_f32 v15, -v148, v76, v15
	v_fma_f32 v15, -v149, v77, v15
	v_fma_f32 v15, -v150, v78, v15
	v_fma_f32 v15, -v151, v79, v15
	s_waitcnt lgkmcnt(0)
	v_fma_f32 v20, -v152, v76, v20
	v_fma_f32 v20, -v153, v77, v20
	v_fma_f32 v20, -v154, v78, v20
	v_fma_f32 v20, -v155, v79, v20
	ds_write_b32 v8, v13 offset:4160
	ds_write_b32 v8, v14 offset:4420
	ds_write_b32 v8, v15 offset:4680
	ds_write_b32 v8, v20 offset:4940
	ds_read_b32 v31, v9 offset:4160
	ds_read_b32 v32, v9 offset:4420
	ds_read_b32 v33, v9 offset:4680
	ds_read_b32 v34, v9 offset:4940
	ds_read_b32 v35, v9 offset:5200
	ds_read_b32 v36, v9 offset:5460
	ds_read_b32 v37, v9 offset:5720
	ds_read_b32 v38, v9 offset:5980
	ds_read_b32 v39, v9 offset:6240
	ds_read_b32 v40, v9 offset:6500
	ds_read_b32 v41, v9 offset:6760
	s_waitcnt lgkmcnt(14)
	ds_read_b32 v42, v9 offset:7020
	s_waitcnt lgkmcnt(14)
	ds_read_b32 v43, v9 offset:7280
	s_waitcnt lgkmcnt(14)
	ds_read_b32 v44, v9 offset:7540
	s_waitcnt lgkmcnt(14)
	ds_read_b32 v45, v9 offset:7800
	s_waitcnt lgkmcnt(14)
	ds_read_b32 v46, v9 offset:8060
	s_waitcnt lgkmcnt(12)
	ds_read_b128 v[214:217], v12 offset:4688
	ds_read_b128 v[230:233], v12 offset:4960
	v_mov_b32_e32 v80, v31
	ds_read_b128 v[198:201], v12 offset:5232
	s_waitcnt lgkmcnt(2)
	v_fma_f32 v81, -v214, v80, v32
	ds_read_b128 v[214:217], v12 offset:5504
	s_waitcnt lgkmcnt(2)
	v_fma_f32 v82, -v230, v80, v33
	v_fma_f32 v82, -v231, v81, v82
	ds_read_b128 v[230:233], v12 offset:5776
	ds_read_b128 v[234:237], v12 offset:5792
	s_waitcnt lgkmcnt(3)
	v_fma_f32 v83, -v198, v80, v34
	v_fma_f32 v83, -v199, v81, v83
	v_fma_f32 v83, -v200, v82, v83
	ds_read_b128 v[198:201], v12 offset:6048
	ds_read_b128 v[202:205], v12 offset:6064
	s_waitcnt lgkmcnt(4)
	v_fma_f32 v84, -v214, v80, v35
	v_fma_f32 v84, -v215, v81, v84
	v_fma_f32 v84, -v216, v82, v84
	v_fma_f32 v84, -v217, v83, v84
	ds_read_b128 v[214:217], v12 offset:6320
	ds_read_b128 v[218:221], v12 offset:6336
	s_waitcnt lgkmcnt(5)
	v_fma_f32 v85, -v230, v80, v36
	v_fma_f32 v85, -v231, v81, v85
	v_fma_f32 v85, -v232, v82, v85
	v_fma_f32 v85, -v233, v83, v85
	s_waitcnt lgkmcnt(4)
	v_fma_f32 v85, -v234, v84, v85
	ds_read_b128 v[230:233], v12 offset:6592
	ds_read_b128 v[234:237], v12 offset:6608
	s_waitcnt lgkmcnt(5)
	v_fma_f32 v86, -v198, v80, v37
	v_fma_f32 v86, -v199, v81, v86
	v_fma_f32 v86, -v200, v82, v86
	v_fma_f32 v86, -v201, v83, v86
	s_waitcnt lgkmcnt(4)
	v_fma_f32 v86, -v202, v84, v86
	v_fma_f32 v86, -v203, v85, v86
	ds_read_b128 v[198:201], v12 offset:6864
	ds_read_b128 v[202:205], v12 offset:6880
	ds_read_b128 v[206:209], v12 offset:6896
	s_waitcnt lgkmcnt(6)
	v_fma_f32 v87, -v214, v80, v38
	v_fma_f32 v87, -v215, v81, v87
	v_fma_f32 v87, -v216, v82, v87
	v_fma_f32 v87, -v217, v83, v87
	s_waitcnt lgkmcnt(5)
	v_fma_f32 v87, -v218, v84, v87
	v_fma_f32 v87, -v219, v85, v87
	v_fma_f32 v87, -v220, v86, v87
	ds_read_b128 v[214:217], v12 offset:7136
	ds_read_b128 v[218:221], v12 offset:7152
	ds_read_b128 v[222:225], v12 offset:7168
	s_waitcnt lgkmcnt(7)
	v_fma_f32 v88, -v230, v80, v39
	v_fma_f32 v88, -v231, v81, v88
	v_fma_f32 v88, -v232, v82, v88
	v_fma_f32 v88, -v233, v83, v88
	s_waitcnt lgkmcnt(6)
	v_fma_f32 v88, -v234, v84, v88
	v_fma_f32 v88, -v235, v85, v88
	v_fma_f32 v88, -v236, v86, v88
	v_fma_f32 v88, -v237, v87, v88
	ds_read_b128 v[230:233], v12 offset:7408
	ds_read_b128 v[234:237], v12 offset:7424
	ds_read_b128 v[156:159], v12 offset:7440
	s_waitcnt lgkmcnt(8)
	v_fma_f32 v89, -v198, v80, v40
	v_fma_f32 v89, -v199, v81, v89
	v_fma_f32 v89, -v200, v82, v89
	v_fma_f32 v89, -v201, v83, v89
	s_waitcnt lgkmcnt(7)
	v_fma_f32 v89, -v202, v84, v89
	v_fma_f32 v89, -v203, v85, v89
	v_fma_f32 v89, -v204, v86, v89
	v_fma_f32 v89, -v205, v87, v89
	s_waitcnt lgkmcnt(6)
	v_fma_f32 v89, -v206, v88, v89
	ds_read_b128 v[198:201], v12 offset:7680
	ds_read_b128 v[202:205], v12 offset:7696
	ds_read_b128 v[206:209], v12 offset:7712
	s_waitcnt lgkmcnt(8)
	v_fma_f32 v90, -v214, v80, v41
	v_fma_f32 v90, -v215, v81, v90
	v_fma_f32 v90, -v216, v82, v90
	v_fma_f32 v90, -v217, v83, v90
	s_waitcnt lgkmcnt(7)
	v_fma_f32 v90, -v218, v84, v90
	v_fma_f32 v90, -v219, v85, v90
	v_fma_f32 v90, -v220, v86, v90
	v_fma_f32 v90, -v221, v87, v90
	s_waitcnt lgkmcnt(6)
	v_fma_f32 v90, -v222, v88, v90
	v_fma_f32 v90, -v223, v89, v90
	ds_read_b128 v[214:217], v12 offset:7952
	ds_read_b128 v[218:221], v12 offset:7968
	ds_read_b128 v[222:225], v12 offset:7984
	ds_read_b128 v[226:229], v12 offset:8000
	s_waitcnt lgkmcnt(9)
	v_fma_f32 v91, -v230, v80, v42
	v_fma_f32 v91, -v231, v81, v91
	v_fma_f32 v91, -v232, v82, v91
	v_fma_f32 v91, -v233, v83, v91
	s_waitcnt lgkmcnt(8)
	v_fma_f32 v91, -v234, v84, v91
	v_fma_f32 v91, -v235, v85, v91
	v_fma_f32 v91, -v236, v86, v91
	v_fma_f32 v91, -v237, v87, v91
	s_waitcnt lgkmcnt(7)
	v_fma_f32 v91, -v156, v88, v91
	v_fma_f32 v91, -v157, v89, v91
	v_fma_f32 v91, -v158, v90, v91
	ds_read_b128 v[230:233], v12 offset:8224
	ds_read_b128 v[234:237], v12 offset:8240
	ds_read_b128 v[156:159], v12 offset:8256
	ds_read_b128 v[164:167], v12 offset:8272
	s_waitcnt lgkmcnt(10)
	v_fma_f32 v92, -v198, v80, v43
	v_fma_f32 v92, -v199, v81, v92
	v_fma_f32 v92, -v200, v82, v92
	v_fma_f32 v92, -v201, v83, v92
	s_waitcnt lgkmcnt(9)
	v_fma_f32 v92, -v202, v84, v92
	v_fma_f32 v92, -v203, v85, v92
	v_fma_f32 v92, -v204, v86, v92
	v_fma_f32 v92, -v205, v87, v92
	s_waitcnt lgkmcnt(8)
	v_fma_f32 v92, -v206, v88, v92
	v_fma_f32 v92, -v207, v89, v92
	v_fma_f32 v92, -v208, v90, v92
	v_fma_f32 v92, -v209, v91, v92
	ds_read_b128 v[198:201], v12 offset:8496
	ds_read_b128 v[202:205], v12 offset:8512
	ds_read_b128 v[206:209], v12 offset:8528
	ds_read_b128 v[210:213], v12 offset:8544
	s_waitcnt lgkmcnt(11)
	v_fma_f32 v93, -v214, v80, v44
	v_fma_f32 v93, -v215, v81, v93
	v_fma_f32 v93, -v216, v82, v93
	v_fma_f32 v93, -v217, v83, v93
	s_waitcnt lgkmcnt(10)
	v_fma_f32 v93, -v218, v84, v93
	v_fma_f32 v93, -v219, v85, v93
	v_fma_f32 v93, -v220, v86, v93
	v_fma_f32 v93, -v221, v87, v93
	s_waitcnt lgkmcnt(9)
	v_fma_f32 v93, -v222, v88, v93
	v_fma_f32 v93, -v223, v89, v93
	v_fma_f32 v93, -v224, v90, v93
	v_fma_f32 v93, -v225, v91, v93
	s_waitcnt lgkmcnt(8)
	v_fma_f32 v93, -v226, v92, v93
	s_waitcnt lgkmcnt(7)
	v_fma_f32 v94, -v230, v80, v45
	v_fma_f32 v94, -v231, v81, v94
	v_fma_f32 v94, -v232, v82, v94
	v_fma_f32 v94, -v233, v83, v94
	s_waitcnt lgkmcnt(6)
	v_fma_f32 v94, -v234, v84, v94
	v_fma_f32 v94, -v235, v85, v94
	v_fma_f32 v94, -v236, v86, v94
	v_fma_f32 v94, -v237, v87, v94
	s_waitcnt lgkmcnt(5)
	v_fma_f32 v94, -v156, v88, v94
	v_fma_f32 v94, -v157, v89, v94
	v_fma_f32 v94, -v158, v90, v94
	v_fma_f32 v94, -v159, v91, v94
	s_waitcnt lgkmcnt(4)
	v_fma_f32 v94, -v164, v92, v94
	v_fma_f32 v94, -v165, v93, v94
	s_waitcnt lgkmcnt(3)
	v_fma_f32 v95, -v198, v80, v46
	v_fma_f32 v95, -v199, v81, v95
	v_fma_f32 v95, -v200, v82, v95
	v_fma_f32 v95, -v201, v83, v95
	s_waitcnt lgkmcnt(2)
	v_fma_f32 v95, -v202, v84, v95
	v_fma_f32 v95, -v203, v85, v95
	v_fma_f32 v95, -v204, v86, v95
	v_fma_f32 v95, -v205, v87, v95
	s_waitcnt lgkmcnt(1)
	v_fma_f32 v95, -v206, v88, v95
	v_fma_f32 v95, -v207, v89, v95
	v_fma_f32 v95, -v208, v90, v95
	v_fma_f32 v95, -v209, v91, v95
	s_waitcnt lgkmcnt(0)
	v_fma_f32 v95, -v210, v92, v95
	v_fma_f32 v95, -v211, v93, v95
	v_fma_f32 v95, -v212, v94, v95
	s_mov_b64 exec, 0xffff
	ds_write_b32 v9, v80 offset:4160
	ds_write_b32 v9, v81 offset:4420
	ds_write_b32 v9, v82 offset:4680
	ds_write_b32 v9, v83 offset:4940
	ds_write_b32 v9, v84 offset:5200
	ds_write_b32 v9, v85 offset:5460
	ds_write_b32 v9, v86 offset:5720
	ds_write_b32 v9, v87 offset:5980
	ds_write_b32 v9, v88 offset:6240
	ds_write_b32 v9, v89 offset:6500
	ds_write_b32 v9, v90 offset:6760
	ds_write_b32 v9, v91 offset:7020
	ds_write_b32 v9, v92 offset:7280
	ds_write_b32 v9, v93 offset:7540
	ds_write_b32 v9, v94 offset:7800
	s_waitcnt lgkmcnt(14)
	ds_write_b32 v9, v95 offset:8060
	s_mov_b64 exec, s[6:7]
	s_waitcnt lgkmcnt(0)
	ds_read_b32 v21, v8 offset:8320
	ds_read_b32 v22, v8 offset:8580
	ds_read_b32 v23, v8 offset:8840
	ds_read_b32 v24, v8 offset:9100
	ds_read_b32 v27, v10 offset:128
	ds_read_b32 v28, v10 offset:132
	ds_read_b32 v29, v10 offset:136
	ds_read_b32 v30, v10 offset:140
	ds_read_b128 v[124:127], v11 offset:8704
	ds_read_b128 v[128:131], v11 offset:8976
	ds_read_b128 v[132:135], v11 offset:9248
	ds_read_b128 v[136:139], v11 offset:9520
	ds_read_b128 v[140:143], v11 offset:8720
	ds_read_b128 v[144:147], v11 offset:8992
	ds_read_b128 v[148:151], v11 offset:9264
	s_waitcnt lgkmcnt(14)
	s_waitcnt lgkmcnt(10)
	v_mul_f32_e32 v13, v21, v27
	s_waitcnt lgkmcnt(9)
	v_mul_f32_e32 v14, v22, v28
	s_waitcnt lgkmcnt(8)
	v_mul_f32_e32 v15, v23, v29
	s_waitcnt lgkmcnt(7)
	v_mul_f32_e32 v20, v24, v30
	ds_read_b128 v[152:155], v11 offset:9536
	s_waitcnt lgkmcnt(7)
	v_fma_f32 v13, -v124, v64, v13
	v_fma_f32 v13, -v125, v65, v13
	v_fma_f32 v13, -v126, v66, v13
	v_fma_f32 v13, -v127, v67, v13
	ds_read_b128 v[124:127], v11 offset:8736
	s_waitcnt lgkmcnt(7)
	v_fma_f32 v14, -v128, v64, v14
	v_fma_f32 v14, -v129, v65, v14
	v_fma_f32 v14, -v130, v66, v14
	v_fma_f32 v14, -v131, v67, v14
	ds_read_b128 v[128:131], v11 offset:9008
	s_waitcnt lgkmcnt(7)
	v_fma_f32 v15, -v132, v64, v15
	v_fma_f32 v15, -v133, v65, v15
	v_fma_f32 v15, -v134, v66, v15
	v_fma_f32 v15, -v135, v67, v15
	ds_read_b128 v[132:135], v11 offset:9280
	s_waitcnt lgkmcnt(7)
	v_fma_f32 v20, -v136, v64, v20
	v_fma_f32 v20, -v137, v65, v20
	v_fma_f32 v20, -v138, v66, v20
	v_fma_f32 v20, -v139, v67, v20
	ds_read_b128 v[136:139], v11 offset:9552
	s_waitcnt lgkmcnt(7)
	v_fma_f32 v13, -v140, v68, v13
	v_fma_f32 v13, -v141, v69, v13
	v_fma_f32 v13, -v142, v70, v13
	v_fma_f32 v13, -v143, v71, v13
	ds_read_b128 v[140:143], v11 offset:8752
	s_waitcnt lgkmcnt(7)
	v_fma_f32 v14, -v144, v68, v14
	v_fma_f32 v14, -v145, v69, v14
	v_fma_f32 v14, -v146, v70, v14
	v_fma_f32 v14, -v147, v71, v14
	ds_read_b128 v[144:147], v11 offset:9024
	s_waitcnt lgkmcnt(7)
	v_fma_f32 v15, -v148, v68, v15
	v_fma_f32 v15, -v149, v69, v15
	v_fma_f32 v15, -v150, v70, v15
	v_fma_f32 v15, -v151, v71, v15
	ds_read_b128 v[148:151], v11 offset:9296
	s_waitcnt lgkmcnt(7)
	v_fma_f32 v20, -v152, v68, v20
	v_fma_f32 v20, -v153, v69, v20
	v_fma_f32 v20, -v154, v70, v20
	v_fma_f32 v20, -v155, v71, v20
	ds_read_b128 v[152:155], v11 offset:9568
	s_waitcnt lgkmcnt(7)
	v_fma_f32 v13, -v124, v72, v13
	v_fma_f32 v13, -v125, v73, v13
	v_fma_f32 v13, -v126, v74, v13
	v_fma_f32 v13, -v127, v75, v13
	ds_read_b128 v[124:127], v11 offset:8768
	s_waitcnt lgkmcnt(7)
	v_fma_f32 v14, -v128, v72, v14
	v_fma_f32 v14, -v129, v73, v14
	v_fma_f32 v14, -v130, v74, v14
	v_fma_f32 v14, -v131, v75, v14
	ds_read_b128 v[128:131], v11 offset:9040
	s_waitcnt lgkmcnt(7)
	v_fma_f32 v15, -v132, v72, v15
	v_fma_f32 v15, -v133, v73, v15
	v_fma_f32 v15, -v134, v74, v15
	v_fma_f32 v15, -v135, v75, v15
	ds_read_b128 v[132:135], v11 offset:9312
	s_waitcnt lgkmcnt(7)
	v_fma_f32 v20, -v136, v72, v20
	v_fma_f32 v20, -v137, v73, v20
	v_fma_f32 v20, -v138, v74, v20
	v_fma_f32 v20, -v139, v75, v20
	ds_read_b128 v[136:139], v11 offset:9584
	s_waitcnt lgkmcnt(7)
	v_fma_f32 v13, -v140, v76, v13
	v_fma_f32 v13, -v141, v77, v13
	v_fma_f32 v13, -v142, v78, v13
	v_fma_f32 v13, -v143, v79, v13
	ds_read_b128 v[140:143], v11 offset:8784
	s_waitcnt lgkmcnt(7)
	v_fma_f32 v14, -v144, v76, v14
	v_fma_f32 v14, -v145, v77, v14
	v_fma_f32 v14, -v146, v78, v14
	v_fma_f32 v14, -v147, v79, v14
	ds_read_b128 v[144:147], v11 offset:9056
	s_waitcnt lgkmcnt(7)
	v_fma_f32 v15, -v148, v76, v15
	v_fma_f32 v15, -v149, v77, v15
	v_fma_f32 v15, -v150, v78, v15
	v_fma_f32 v15, -v151, v79, v15
	ds_read_b128 v[148:151], v11 offset:9328
	s_waitcnt lgkmcnt(7)
	v_fma_f32 v20, -v152, v76, v20
	v_fma_f32 v20, -v153, v77, v20
	v_fma_f32 v20, -v154, v78, v20
	v_fma_f32 v20, -v155, v79, v20
	ds_read_b128 v[152:155], v11 offset:9600
	s_waitcnt lgkmcnt(7)
	v_fma_f32 v13, -v124, v80, v13
	v_fma_f32 v13, -v125, v81, v13
	v_fma_f32 v13, -v126, v82, v13
	v_fma_f32 v13, -v127, v83, v13
	ds_read_b128 v[124:127], v11 offset:8800
	s_waitcnt lgkmcnt(7)
	v_fma_f32 v14, -v128, v80, v14
	v_fma_f32 v14, -v129, v81, v14
	v_fma_f32 v14, -v130, v82, v14
	v_fma_f32 v14, -v131, v83, v14
	ds_read_b128 v[128:131], v11 offset:9072
	s_waitcnt lgkmcnt(7)
	v_fma_f32 v15, -v132, v80, v15
	v_fma_f32 v15, -v133, v81, v15
	v_fma_f32 v15, -v134, v82, v15
	v_fma_f32 v15, -v135, v83, v15
	ds_read_b128 v[132:135], v11 offset:9344
	s_waitcnt lgkmcnt(7)
	v_fma_f32 v20, -v136, v80, v20
	v_fma_f32 v20, -v137, v81, v20
	v_fma_f32 v20, -v138, v82, v20
	v_fma_f32 v20, -v139, v83, v20
	ds_read_b128 v[136:139], v11 offset:9616
	s_waitcnt lgkmcnt(7)
	v_fma_f32 v13, -v140, v84, v13
	v_fma_f32 v13, -v141, v85, v13
	v_fma_f32 v13, -v142, v86, v13
	v_fma_f32 v13, -v143, v87, v13
	ds_read_b128 v[140:143], v11 offset:8816
	s_waitcnt lgkmcnt(7)
	v_fma_f32 v14, -v144, v84, v14
	v_fma_f32 v14, -v145, v85, v14
	v_fma_f32 v14, -v146, v86, v14
	v_fma_f32 v14, -v147, v87, v14
	ds_read_b128 v[144:147], v11 offset:9088
	s_waitcnt lgkmcnt(7)
	v_fma_f32 v15, -v148, v84, v15
	v_fma_f32 v15, -v149, v85, v15
	v_fma_f32 v15, -v150, v86, v15
	v_fma_f32 v15, -v151, v87, v15
	ds_read_b128 v[148:151], v11 offset:9360
	s_waitcnt lgkmcnt(7)
	v_fma_f32 v20, -v152, v84, v20
	v_fma_f32 v20, -v153, v85, v20
	v_fma_f32 v20, -v154, v86, v20
	v_fma_f32 v20, -v155, v87, v20
	ds_read_b128 v[152:155], v11 offset:9632
	s_waitcnt lgkmcnt(7)
	v_fma_f32 v13, -v124, v88, v13
	v_fma_f32 v13, -v125, v89, v13
	v_fma_f32 v13, -v126, v90, v13
	v_fma_f32 v13, -v127, v91, v13
	s_waitcnt lgkmcnt(6)
	v_fma_f32 v14, -v128, v88, v14
	v_fma_f32 v14, -v129, v89, v14
	v_fma_f32 v14, -v130, v90, v14
	v_fma_f32 v14, -v131, v91, v14
	s_waitcnt lgkmcnt(5)
	v_fma_f32 v15, -v132, v88, v15
	v_fma_f32 v15, -v133, v89, v15
	v_fma_f32 v15, -v134, v90, v15
	v_fma_f32 v15, -v135, v91, v15
	s_waitcnt lgkmcnt(4)
	v_fma_f32 v20, -v136, v88, v20
	v_fma_f32 v20, -v137, v89, v20
	v_fma_f32 v20, -v138, v90, v20
	v_fma_f32 v20, -v139, v91, v20
	s_waitcnt lgkmcnt(3)
	v_fma_f32 v13, -v140, v92, v13
	v_fma_f32 v13, -v141, v93, v13
	v_fma_f32 v13, -v142, v94, v13
	v_fma_f32 v13, -v143, v95, v13
	s_waitcnt lgkmcnt(2)
	v_fma_f32 v14, -v144, v92, v14
	v_fma_f32 v14, -v145, v93, v14
	v_fma_f32 v14, -v146, v94, v14
	v_fma_f32 v14, -v147, v95, v14
	s_waitcnt lgkmcnt(1)
	v_fma_f32 v15, -v148, v92, v15
	v_fma_f32 v15, -v149, v93, v15
	v_fma_f32 v15, -v150, v94, v15
	v_fma_f32 v15, -v151, v95, v15
	s_waitcnt lgkmcnt(0)
	v_fma_f32 v20, -v152, v92, v20
	v_fma_f32 v20, -v153, v93, v20
	v_fma_f32 v20, -v154, v94, v20
	v_fma_f32 v20, -v155, v95, v20
	ds_write_b32 v8, v13 offset:8320
	ds_write_b32 v8, v14 offset:8580
	ds_write_b32 v8, v15 offset:8840
	ds_write_b32 v8, v20 offset:9100
	ds_read_b32 v31, v9 offset:8320
	ds_read_b32 v32, v9 offset:8580
	ds_read_b32 v33, v9 offset:8840
	ds_read_b32 v34, v9 offset:9100
	ds_read_b32 v35, v9 offset:9360
	ds_read_b32 v36, v9 offset:9620
	ds_read_b32 v37, v9 offset:9880
	ds_read_b32 v38, v9 offset:10140
	ds_read_b32 v39, v9 offset:10400
	ds_read_b32 v40, v9 offset:10660
	ds_read_b32 v41, v9 offset:10920
	s_waitcnt lgkmcnt(14)
	ds_read_b32 v42, v9 offset:11180
	s_waitcnt lgkmcnt(14)
	ds_read_b32 v43, v9 offset:11440
	s_waitcnt lgkmcnt(14)
	ds_read_b32 v44, v9 offset:11700
	s_waitcnt lgkmcnt(14)
	ds_read_b32 v45, v9 offset:11960
	s_waitcnt lgkmcnt(14)
	ds_read_b32 v46, v9 offset:12220
	s_waitcnt lgkmcnt(12)
	ds_read_b128 v[214:217], v12 offset:9104
	ds_read_b128 v[230:233], v12 offset:9376
	v_mov_b32_e32 v96, v31
	ds_read_b128 v[198:201], v12 offset:9648
	s_waitcnt lgkmcnt(2)
	v_fma_f32 v97, -v214, v96, v32
	ds_read_b128 v[214:217], v12 offset:9920
	s_waitcnt lgkmcnt(2)
	v_fma_f32 v98, -v230, v96, v33
	v_fma_f32 v98, -v231, v97, v98
	ds_read_b128 v[230:233], v12 offset:10192
	ds_read_b128 v[234:237], v12 offset:10208
	s_waitcnt lgkmcnt(3)
	v_fma_f32 v99, -v198, v96, v34
	v_fma_f32 v99, -v199, v97, v99
	v_fma_f32 v99, -v200, v98, v99
	ds_read_b128 v[198:201], v12 offset:10464
	ds_read_b128 v[202:205], v12 offset:10480
	s_waitcnt lgkmcnt(4)
	v_fma_f32 v100, -v214, v96, v35
	v_fma_f32 v100, -v215, v97, v100
	v_fma_f32 v100, -v216, v98, v100
	v_fma_f32 v100, -v217, v99, v100
	ds_read_b128 v[214:217], v12 offset:10736
	ds_read_b128 v[218:221], v12 offset:10752
	s_waitcnt lgkmcnt(5)
	v_fma_f32 v101, -v230, v96, v36
	v_fma_f32 v101, -v231, v97, v101
	v_fma_f32 v101, -v232, v98, v101
	v_fma_f32 v101, -v233, v99, v101
	s_waitcnt lgkmcnt(4)
	v_fma_f32 v101, -v234, v100, v101
	ds_read_b128 v[230:233], v12 offset:11008
	ds_read_b128 v[234:237], v12 offset:11024
	s_waitcnt lgkmcnt(5)
	v_fma_f32 v102, -v198, v96, v37
	v_fma_f32 v102, -v199, v97, v102
	v_fma_f32 v102, -v200, v98, v102
	v_fma_f32 v102, -v201, v99, v102
	s_waitcnt lgkmcnt(4)
	v_fma_f32 v102, -v202, v100, v102
	v_fma_f32 v102, -v203, v101, v102
	ds_read_b128 v[198:201], v12 offset:11280
	ds_read_b128 v[202:205], v12 offset:11296
	ds_read_b128 v[206:209], v12 offset:11312
	s_waitcnt lgkmcnt(6)
	v_fma_f32 v103, -v214, v96, v38
	v_fma_f32 v103, -v215, v97, v103
	v_fma_f32 v103, -v216, v98, v103
	v_fma_f32 v103, -v217, v99, v103
	s_waitcnt lgkmcnt(5)
	v_fma_f32 v103, -v218, v100, v103
	v_fma_f32 v103, -v219, v101, v103
	v_fma_f32 v103, -v220, v102, v103
	ds_read_b128 v[214:217], v12 offset:11552
	ds_read_b128 v[218:221], v12 offset:11568
	ds_read_b128 v[222:225], v12 offset:11584
	s_waitcnt lgkmcnt(7)
	v_fma_f32 v104, -v230, v96, v39
	v_fma_f32 v104, -v231, v97, v104
	v_fma_f32 v104, -v232, v98, v104
	v_fma_f32 v104, -v233, v99, v104
	s_waitcnt lgkmcnt(6)
	v_fma_f32 v104, -v234, v100, v104
	v_fma_f32 v104, -v235, v101, v104
	v_fma_f32 v104, -v236, v102, v104
	v_fma_f32 v104, -v237, v103, v104
	ds_read_b128 v[230:233], v12 offset:11824
	ds_read_b128 v[234:237], v12 offset:11840
	ds_read_b128 v[156:159], v12 offset:11856
	s_waitcnt lgkmcnt(8)
	v_fma_f32 v105, -v198, v96, v40
	v_fma_f32 v105, -v199, v97, v105
	v_fma_f32 v105, -v200, v98, v105
	v_fma_f32 v105, -v201, v99, v105
	s_waitcnt lgkmcnt(7)
	v_fma_f32 v105, -v202, v100, v105
	v_fma_f32 v105, -v203, v101, v105
	v_fma_f32 v105, -v204, v102, v105
	v_fma_f32 v105, -v205, v103, v105
	s_waitcnt lgkmcnt(6)
	v_fma_f32 v105, -v206, v104, v105
	ds_read_b128 v[198:201], v12 offset:12096
	ds_read_b128 v[202:205], v12 offset:12112
	ds_read_b128 v[206:209], v12 offset:12128
	s_waitcnt lgkmcnt(8)
	v_fma_f32 v106, -v214, v96, v41
	v_fma_f32 v106, -v215, v97, v106
	v_fma_f32 v106, -v216, v98, v106
	v_fma_f32 v106, -v217, v99, v106
	s_waitcnt lgkmcnt(7)
	v_fma_f32 v106, -v218, v100, v106
	v_fma_f32 v106, -v219, v101, v106
	v_fma_f32 v106, -v220, v102, v106
	v_fma_f32 v106, -v221, v103, v106
	s_waitcnt lgkmcnt(6)
	v_fma_f32 v106, -v222, v104, v106
	v_fma_f32 v106, -v223, v105, v106
	ds_read_b128 v[214:217], v12 offset:12368
	ds_read_b128 v[218:221], v12 offset:12384
	ds_read_b128 v[222:225], v12 offset:12400
	ds_read_b128 v[226:229], v12 offset:12416
	s_waitcnt lgkmcnt(9)
	v_fma_f32 v107, -v230, v96, v42
	v_fma_f32 v107, -v231, v97, v107
	v_fma_f32 v107, -v232, v98, v107
	v_fma_f32 v107, -v233, v99, v107
	s_waitcnt lgkmcnt(8)
	v_fma_f32 v107, -v234, v100, v107
	v_fma_f32 v107, -v235, v101, v107
	v_fma_f32 v107, -v236, v102, v107
	v_fma_f32 v107, -v237, v103, v107
	s_waitcnt lgkmcnt(7)
	v_fma_f32 v107, -v156, v104, v107
	v_fma_f32 v107, -v157, v105, v107
	v_fma_f32 v107, -v158, v106, v107
	ds_read_b128 v[230:233], v12 offset:12640
	ds_read_b128 v[234:237], v12 offset:12656
	ds_read_b128 v[156:159], v12 offset:12672
	ds_read_b128 v[164:167], v12 offset:12688
	s_waitcnt lgkmcnt(10)
	v_fma_f32 v108, -v198, v96, v43
	v_fma_f32 v108, -v199, v97, v108
	v_fma_f32 v108, -v200, v98, v108
	v_fma_f32 v108, -v201, v99, v108
	s_waitcnt lgkmcnt(9)
	v_fma_f32 v108, -v202, v100, v108
	v_fma_f32 v108, -v203, v101, v108
	v_fma_f32 v108, -v204, v102, v108
	v_fma_f32 v108, -v205, v103, v108
	s_waitcnt lgkmcnt(8)
	v_fma_f32 v108, -v206, v104, v108
	v_fma_f32 v108, -v207, v105, v108
	v_fma_f32 v108, -v208, v106, v108
	v_fma_f32 v108, -v209, v107, v108
	ds_read_b128 v[198:201], v12 offset:12912
	ds_read_b128 v[202:205], v12 offset:12928
	ds_read_b128 v[206:209], v12 offset:12944
	ds_read_b128 v[210:213], v12 offset:12960
	s_waitcnt lgkmcnt(11)
	v_fma_f32 v109, -v214, v96, v44
	v_fma_f32 v109, -v215, v97, v109
	v_fma_f32 v109, -v216, v98, v109
	v_fma_f32 v109, -v217, v99, v109
	s_waitcnt lgkmcnt(10)
	v_fma_f32 v109, -v218, v100, v109
	v_fma_f32 v109, -v219, v101, v109
	v_fma_f32 v109, -v220, v102, v109
	v_fma_f32 v109, -v221, v103, v109
	s_waitcnt lgkmcnt(9)
	v_fma_f32 v109, -v222, v104, v109
	v_fma_f32 v109, -v223, v105, v109
	v_fma_f32 v109, -v224, v106, v109
	v_fma_f32 v109, -v225, v107, v109
	s_waitcnt lgkmcnt(8)
	v_fma_f32 v109, -v226, v108, v109
	s_waitcnt lgkmcnt(7)
	v_fma_f32 v110, -v230, v96, v45
	v_fma_f32 v110, -v231, v97, v110
	v_fma_f32 v110, -v232, v98, v110
	v_fma_f32 v110, -v233, v99, v110
	s_waitcnt lgkmcnt(6)
	v_fma_f32 v110, -v234, v100, v110
	v_fma_f32 v110, -v235, v101, v110
	v_fma_f32 v110, -v236, v102, v110
	v_fma_f32 v110, -v237, v103, v110
	s_waitcnt lgkmcnt(5)
	v_fma_f32 v110, -v156, v104, v110
	v_fma_f32 v110, -v157, v105, v110
	v_fma_f32 v110, -v158, v106, v110
	v_fma_f32 v110, -v159, v107, v110
	s_waitcnt lgkmcnt(4)
	v_fma_f32 v110, -v164, v108, v110
	v_fma_f32 v110, -v165, v109, v110
	s_waitcnt lgkmcnt(3)
	v_fma_f32 v111, -v198, v96, v46
	v_fma_f32 v111, -v199, v97, v111
	v_fma_f32 v111, -v200, v98, v111
	v_fma_f32 v111, -v201, v99, v111
	s_waitcnt lgkmcnt(2)
	v_fma_f32 v111, -v202, v100, v111
	v_fma_f32 v111, -v203, v101, v111
	v_fma_f32 v111, -v204, v102, v111
	v_fma_f32 v111, -v205, v103, v111
	s_waitcnt lgkmcnt(1)
	v_fma_f32 v111, -v206, v104, v111
	v_fma_f32 v111, -v207, v105, v111
	v_fma_f32 v111, -v208, v106, v111
	v_fma_f32 v111, -v209, v107, v111
	s_waitcnt lgkmcnt(0)
	v_fma_f32 v111, -v210, v108, v111
	v_fma_f32 v111, -v211, v109, v111
	v_fma_f32 v111, -v212, v110, v111
	s_mov_b64 exec, 0xffff
	ds_write_b32 v9, v96 offset:8320
	ds_write_b32 v9, v97 offset:8580
	ds_write_b32 v9, v98 offset:8840
	ds_write_b32 v9, v99 offset:9100
	ds_write_b32 v9, v100 offset:9360
	ds_write_b32 v9, v101 offset:9620
	ds_write_b32 v9, v102 offset:9880
	ds_write_b32 v9, v103 offset:10140
	ds_write_b32 v9, v104 offset:10400
	ds_write_b32 v9, v105 offset:10660
	ds_write_b32 v9, v106 offset:10920
	ds_write_b32 v9, v107 offset:11180
	ds_write_b32 v9, v108 offset:11440
	ds_write_b32 v9, v109 offset:11700
	ds_write_b32 v9, v110 offset:11960
	s_waitcnt lgkmcnt(14)
	ds_write_b32 v9, v111 offset:12220
	s_mov_b64 exec, s[6:7]
	s_waitcnt lgkmcnt(0)
	ds_read_b32 v21, v8 offset:12480
	ds_read_b32 v22, v8 offset:12740
	ds_read_b32 v23, v8 offset:13000
	ds_read_b32 v24, v8 offset:13260
	ds_read_b32 v27, v10 offset:192
	ds_read_b32 v28, v10 offset:196
	ds_read_b32 v29, v10 offset:200
	ds_read_b32 v30, v10 offset:204
	ds_read_b128 v[124:127], v11 offset:13056
	ds_read_b128 v[128:131], v11 offset:13328
	ds_read_b128 v[132:135], v11 offset:13600
	ds_read_b128 v[136:139], v11 offset:13872
	ds_read_b128 v[140:143], v11 offset:13072
	ds_read_b128 v[144:147], v11 offset:13344
	ds_read_b128 v[148:151], v11 offset:13616
	s_waitcnt lgkmcnt(14)
	s_waitcnt lgkmcnt(10)
	v_mul_f32_e32 v13, v21, v27
	s_waitcnt lgkmcnt(9)
	v_mul_f32_e32 v14, v22, v28
	s_waitcnt lgkmcnt(8)
	v_mul_f32_e32 v15, v23, v29
	s_waitcnt lgkmcnt(7)
	v_mul_f32_e32 v20, v24, v30
	ds_read_b128 v[152:155], v11 offset:13888
	s_waitcnt lgkmcnt(7)
	v_fma_f32 v13, -v124, v64, v13
	v_fma_f32 v13, -v125, v65, v13
	v_fma_f32 v13, -v126, v66, v13
	v_fma_f32 v13, -v127, v67, v13
	ds_read_b128 v[124:127], v11 offset:13088
	s_waitcnt lgkmcnt(7)
	v_fma_f32 v14, -v128, v64, v14
	v_fma_f32 v14, -v129, v65, v14
	v_fma_f32 v14, -v130, v66, v14
	v_fma_f32 v14, -v131, v67, v14
	ds_read_b128 v[128:131], v11 offset:13360
	s_waitcnt lgkmcnt(7)
	v_fma_f32 v15, -v132, v64, v15
	v_fma_f32 v15, -v133, v65, v15
	v_fma_f32 v15, -v134, v66, v15
	v_fma_f32 v15, -v135, v67, v15
	ds_read_b128 v[132:135], v11 offset:13632
	s_waitcnt lgkmcnt(7)
	v_fma_f32 v20, -v136, v64, v20
	v_fma_f32 v20, -v137, v65, v20
	v_fma_f32 v20, -v138, v66, v20
	v_fma_f32 v20, -v139, v67, v20
	ds_read_b128 v[136:139], v11 offset:13904
	s_waitcnt lgkmcnt(7)
	v_fma_f32 v13, -v140, v68, v13
	v_fma_f32 v13, -v141, v69, v13
	v_fma_f32 v13, -v142, v70, v13
	v_fma_f32 v13, -v143, v71, v13
	ds_read_b128 v[140:143], v11 offset:13104
	s_waitcnt lgkmcnt(7)
	v_fma_f32 v14, -v144, v68, v14
	v_fma_f32 v14, -v145, v69, v14
	v_fma_f32 v14, -v146, v70, v14
	v_fma_f32 v14, -v147, v71, v14
	ds_read_b128 v[144:147], v11 offset:13376
	s_waitcnt lgkmcnt(7)
	v_fma_f32 v15, -v148, v68, v15
	v_fma_f32 v15, -v149, v69, v15
	v_fma_f32 v15, -v150, v70, v15
	v_fma_f32 v15, -v151, v71, v15
	ds_read_b128 v[148:151], v11 offset:13648
	s_waitcnt lgkmcnt(7)
	v_fma_f32 v20, -v152, v68, v20
	v_fma_f32 v20, -v153, v69, v20
	v_fma_f32 v20, -v154, v70, v20
	v_fma_f32 v20, -v155, v71, v20
	ds_read_b128 v[152:155], v11 offset:13920
	s_waitcnt lgkmcnt(7)
	v_fma_f32 v13, -v124, v72, v13
	v_fma_f32 v13, -v125, v73, v13
	v_fma_f32 v13, -v126, v74, v13
	v_fma_f32 v13, -v127, v75, v13
	ds_read_b128 v[124:127], v11 offset:13120
	s_waitcnt lgkmcnt(7)
	v_fma_f32 v14, -v128, v72, v14
	v_fma_f32 v14, -v129, v73, v14
	v_fma_f32 v14, -v130, v74, v14
	v_fma_f32 v14, -v131, v75, v14
	ds_read_b128 v[128:131], v11 offset:13392
	s_waitcnt lgkmcnt(7)
	v_fma_f32 v15, -v132, v72, v15
	v_fma_f32 v15, -v133, v73, v15
	v_fma_f32 v15, -v134, v74, v15
	v_fma_f32 v15, -v135, v75, v15
	ds_read_b128 v[132:135], v11 offset:13664
	s_waitcnt lgkmcnt(7)
	v_fma_f32 v20, -v136, v72, v20
	v_fma_f32 v20, -v137, v73, v20
	v_fma_f32 v20, -v138, v74, v20
	v_fma_f32 v20, -v139, v75, v20
	ds_read_b128 v[136:139], v11 offset:13936
	s_waitcnt lgkmcnt(7)
	v_fma_f32 v13, -v140, v76, v13
	v_fma_f32 v13, -v141, v77, v13
	v_fma_f32 v13, -v142, v78, v13
	v_fma_f32 v13, -v143, v79, v13
	ds_read_b128 v[140:143], v11 offset:13136
	s_waitcnt lgkmcnt(7)
	v_fma_f32 v14, -v144, v76, v14
	v_fma_f32 v14, -v145, v77, v14
	v_fma_f32 v14, -v146, v78, v14
	v_fma_f32 v14, -v147, v79, v14
	ds_read_b128 v[144:147], v11 offset:13408
	s_waitcnt lgkmcnt(7)
	v_fma_f32 v15, -v148, v76, v15
	v_fma_f32 v15, -v149, v77, v15
	v_fma_f32 v15, -v150, v78, v15
	v_fma_f32 v15, -v151, v79, v15
	ds_read_b128 v[148:151], v11 offset:13680
	s_waitcnt lgkmcnt(7)
	v_fma_f32 v20, -v152, v76, v20
	v_fma_f32 v20, -v153, v77, v20
	v_fma_f32 v20, -v154, v78, v20
	v_fma_f32 v20, -v155, v79, v20
	ds_read_b128 v[152:155], v11 offset:13952
	s_waitcnt lgkmcnt(7)
	v_fma_f32 v13, -v124, v80, v13
	v_fma_f32 v13, -v125, v81, v13
	v_fma_f32 v13, -v126, v82, v13
	v_fma_f32 v13, -v127, v83, v13
	ds_read_b128 v[124:127], v11 offset:13152
	s_waitcnt lgkmcnt(7)
	v_fma_f32 v14, -v128, v80, v14
	v_fma_f32 v14, -v129, v81, v14
	v_fma_f32 v14, -v130, v82, v14
	v_fma_f32 v14, -v131, v83, v14
	ds_read_b128 v[128:131], v11 offset:13424
	s_waitcnt lgkmcnt(7)
	v_fma_f32 v15, -v132, v80, v15
	v_fma_f32 v15, -v133, v81, v15
	v_fma_f32 v15, -v134, v82, v15
	v_fma_f32 v15, -v135, v83, v15
	ds_read_b128 v[132:135], v11 offset:13696
	s_waitcnt lgkmcnt(7)
	v_fma_f32 v20, -v136, v80, v20
	v_fma_f32 v20, -v137, v81, v20
	v_fma_f32 v20, -v138, v82, v20
	v_fma_f32 v20, -v139, v83, v20
	ds_read_b128 v[136:139], v11 offset:13968
	s_waitcnt lgkmcnt(7)
	v_fma_f32 v13, -v140, v84, v13
	v_fma_f32 v13, -v141, v85, v13
	v_fma_f32 v13, -v142, v86, v13
	v_fma_f32 v13, -v143, v87, v13
	ds_read_b128 v[140:143], v11 offset:13168
	s_waitcnt lgkmcnt(7)
	v_fma_f32 v14, -v144, v84, v14
	v_fma_f32 v14, -v145, v85, v14
	v_fma_f32 v14, -v146, v86, v14
	v_fma_f32 v14, -v147, v87, v14
	ds_read_b128 v[144:147], v11 offset:13440
	s_waitcnt lgkmcnt(7)
	v_fma_f32 v15, -v148, v84, v15
	v_fma_f32 v15, -v149, v85, v15
	v_fma_f32 v15, -v150, v86, v15
	v_fma_f32 v15, -v151, v87, v15
	ds_read_b128 v[148:151], v11 offset:13712
	s_waitcnt lgkmcnt(7)
	v_fma_f32 v20, -v152, v84, v20
	v_fma_f32 v20, -v153, v85, v20
	v_fma_f32 v20, -v154, v86, v20
	v_fma_f32 v20, -v155, v87, v20
	ds_read_b128 v[152:155], v11 offset:13984
	s_waitcnt lgkmcnt(7)
	v_fma_f32 v13, -v124, v88, v13
	v_fma_f32 v13, -v125, v89, v13
	v_fma_f32 v13, -v126, v90, v13
	v_fma_f32 v13, -v127, v91, v13
	ds_read_b128 v[124:127], v11 offset:13184
	s_waitcnt lgkmcnt(7)
	v_fma_f32 v14, -v128, v88, v14
	v_fma_f32 v14, -v129, v89, v14
	v_fma_f32 v14, -v130, v90, v14
	v_fma_f32 v14, -v131, v91, v14
	ds_read_b128 v[128:131], v11 offset:13456
	s_waitcnt lgkmcnt(7)
	v_fma_f32 v15, -v132, v88, v15
	v_fma_f32 v15, -v133, v89, v15
	v_fma_f32 v15, -v134, v90, v15
	v_fma_f32 v15, -v135, v91, v15
	ds_read_b128 v[132:135], v11 offset:13728
	s_waitcnt lgkmcnt(7)
	v_fma_f32 v20, -v136, v88, v20
	v_fma_f32 v20, -v137, v89, v20
	v_fma_f32 v20, -v138, v90, v20
	v_fma_f32 v20, -v139, v91, v20
	ds_read_b128 v[136:139], v11 offset:14000
	s_waitcnt lgkmcnt(7)
	v_fma_f32 v13, -v140, v92, v13
	v_fma_f32 v13, -v141, v93, v13
	v_fma_f32 v13, -v142, v94, v13
	v_fma_f32 v13, -v143, v95, v13
	ds_read_b128 v[140:143], v11 offset:13200
	s_waitcnt lgkmcnt(7)
	v_fma_f32 v14, -v144, v92, v14
	v_fma_f32 v14, -v145, v93, v14
	v_fma_f32 v14, -v146, v94, v14
	v_fma_f32 v14, -v147, v95, v14
	ds_read_b128 v[144:147], v11 offset:13472
	s_waitcnt lgkmcnt(7)
	v_fma_f32 v15, -v148, v92, v15
	v_fma_f32 v15, -v149, v93, v15
	v_fma_f32 v15, -v150, v94, v15
	v_fma_f32 v15, -v151, v95, v15
	ds_read_b128 v[148:151], v11 offset:13744
	s_waitcnt lgkmcnt(7)
	v_fma_f32 v20, -v152, v92, v20
	v_fma_f32 v20, -v153, v93, v20
	v_fma_f32 v20, -v154, v94, v20
	v_fma_f32 v20, -v155, v95, v20
	ds_read_b128 v[152:155], v11 offset:14016
	s_waitcnt lgkmcnt(7)
	v_fma_f32 v13, -v124, v96, v13
	v_fma_f32 v13, -v125, v97, v13
	v_fma_f32 v13, -v126, v98, v13
	v_fma_f32 v13, -v127, v99, v13
	ds_read_b128 v[124:127], v11 offset:13216
	s_waitcnt lgkmcnt(7)
	v_fma_f32 v14, -v128, v96, v14
	v_fma_f32 v14, -v129, v97, v14
	v_fma_f32 v14, -v130, v98, v14
	v_fma_f32 v14, -v131, v99, v14
	ds_read_b128 v[128:131], v11 offset:13488
	s_waitcnt lgkmcnt(7)
	v_fma_f32 v15, -v132, v96, v15
	v_fma_f32 v15, -v133, v97, v15
	v_fma_f32 v15, -v134, v98, v15
	v_fma_f32 v15, -v135, v99, v15
	ds_read_b128 v[132:135], v11 offset:13760
	s_waitcnt lgkmcnt(7)
	v_fma_f32 v20, -v136, v96, v20
	v_fma_f32 v20, -v137, v97, v20
	v_fma_f32 v20, -v138, v98, v20
	v_fma_f32 v20, -v139, v99, v20
	ds_read_b128 v[136:139], v11 offset:14032
	s_waitcnt lgkmcnt(7)
	v_fma_f32 v13, -v140, v100, v13
	v_fma_f32 v13, -v141, v101, v13
	v_fma_f32 v13, -v142, v102, v13
	v_fma_f32 v13, -v143, v103, v13
	ds_read_b128 v[140:143], v11 offset:13232
	s_waitcnt lgkmcnt(7)
	v_fma_f32 v14, -v144, v100, v14
	v_fma_f32 v14, -v145, v101, v14
	v_fma_f32 v14, -v146, v102, v14
	v_fma_f32 v14, -v147, v103, v14
	ds_read_b128 v[144:147], v11 offset:13504
	s_waitcnt lgkmcnt(7)
	v_fma_f32 v15, -v148, v100, v15
	v_fma_f32 v15, -v149, v101, v15
	v_fma_f32 v15, -v150, v102, v15
	v_fma_f32 v15, -v151, v103, v15
	ds_read_b128 v[148:151], v11 offset:13776
	s_waitcnt lgkmcnt(7)
	v_fma_f32 v20, -v152, v100, v20
	v_fma_f32 v20, -v153, v101, v20
	v_fma_f32 v20, -v154, v102, v20
	v_fma_f32 v20, -v155, v103, v20
	ds_read_b128 v[152:155], v11 offset:14048
	s_waitcnt lgkmcnt(7)
	v_fma_f32 v13, -v124, v104, v13
	v_fma_f32 v13, -v125, v105, v13
	v_fma_f32 v13, -v126, v106, v13
	v_fma_f32 v13, -v127, v107, v13
	s_waitcnt lgkmcnt(6)
	v_fma_f32 v14, -v128, v104, v14
	v_fma_f32 v14, -v129, v105, v14
	v_fma_f32 v14, -v130, v106, v14
	v_fma_f32 v14, -v131, v107, v14
	s_waitcnt lgkmcnt(5)
	v_fma_f32 v15, -v132, v104, v15
	v_fma_f32 v15, -v133, v105, v15
	v_fma_f32 v15, -v134, v106, v15
	v_fma_f32 v15, -v135, v107, v15
	s_waitcnt lgkmcnt(4)
	v_fma_f32 v20, -v136, v104, v20
	v_fma_f32 v20, -v137, v105, v20
	v_fma_f32 v20, -v138, v106, v20
	v_fma_f32 v20, -v139, v107, v20
	s_waitcnt lgkmcnt(3)
	v_fma_f32 v13, -v140, v108, v13
	v_fma_f32 v13, -v141, v109, v13
	v_fma_f32 v13, -v142, v110, v13
	v_fma_f32 v13, -v143, v111, v13
	s_waitcnt lgkmcnt(2)
	v_fma_f32 v14, -v144, v108, v14
	v_fma_f32 v14, -v145, v109, v14
	v_fma_f32 v14, -v146, v110, v14
	v_fma_f32 v14, -v147, v111, v14
	s_waitcnt lgkmcnt(1)
	v_fma_f32 v15, -v148, v108, v15
	v_fma_f32 v15, -v149, v109, v15
	v_fma_f32 v15, -v150, v110, v15
	v_fma_f32 v15, -v151, v111, v15
	s_waitcnt lgkmcnt(0)
	v_fma_f32 v20, -v152, v108, v20
	v_fma_f32 v20, -v153, v109, v20
	v_fma_f32 v20, -v154, v110, v20
	v_fma_f32 v20, -v155, v111, v20
	ds_write_b32 v8, v13 offset:12480
	ds_write_b32 v8, v14 offset:12740
	ds_write_b32 v8, v15 offset:13000
	ds_write_b32 v8, v20 offset:13260
	ds_read_b32 v31, v9 offset:12480
	ds_read_b32 v32, v9 offset:12740
	ds_read_b32 v33, v9 offset:13000
	ds_read_b32 v34, v9 offset:13260
	ds_read_b32 v35, v9 offset:13520
	ds_read_b32 v36, v9 offset:13780
	ds_read_b32 v37, v9 offset:14040
	ds_read_b32 v38, v9 offset:14300
	ds_read_b32 v39, v9 offset:14560
	ds_read_b32 v40, v9 offset:14820
	ds_read_b32 v41, v9 offset:15080
	s_waitcnt lgkmcnt(14)
	ds_read_b32 v42, v9 offset:15340
	s_waitcnt lgkmcnt(14)
	ds_read_b32 v43, v9 offset:15600
	s_waitcnt lgkmcnt(14)
	ds_read_b32 v44, v9 offset:15860
	s_waitcnt lgkmcnt(14)
	ds_read_b32 v45, v9 offset:16120
	s_waitcnt lgkmcnt(14)
	ds_read_b32 v46, v9 offset:16380
	s_waitcnt lgkmcnt(12)
	ds_read_b128 v[214:217], v12 offset:13520
	ds_read_b128 v[230:233], v12 offset:13792
	v_mov_b32_e32 v112, v31
	ds_read_b128 v[198:201], v12 offset:14064
	s_waitcnt lgkmcnt(2)
	v_fma_f32 v113, -v214, v112, v32
	ds_read_b128 v[214:217], v12 offset:14336
	s_waitcnt lgkmcnt(2)
	v_fma_f32 v114, -v230, v112, v33
	v_fma_f32 v114, -v231, v113, v114
	ds_read_b128 v[230:233], v12 offset:14608
	ds_read_b128 v[234:237], v12 offset:14624
	s_waitcnt lgkmcnt(3)
	v_fma_f32 v115, -v198, v112, v34
	v_fma_f32 v115, -v199, v113, v115
	v_fma_f32 v115, -v200, v114, v115
	ds_read_b128 v[198:201], v12 offset:14880
	ds_read_b128 v[202:205], v12 offset:14896
	s_waitcnt lgkmcnt(4)
	v_fma_f32 v116, -v214, v112, v35
	v_fma_f32 v116, -v215, v113, v116
	v_fma_f32 v116, -v216, v114, v116
	v_fma_f32 v116, -v217, v115, v116
	ds_read_b128 v[214:217], v12 offset:15152
	ds_read_b128 v[218:221], v12 offset:15168
	s_waitcnt lgkmcnt(5)
	v_fma_f32 v117, -v230, v112, v36
	v_fma_f32 v117, -v231, v113, v117
	v_fma_f32 v117, -v232, v114, v117
	v_fma_f32 v117, -v233, v115, v117
	s_waitcnt lgkmcnt(4)
	v_fma_f32 v117, -v234, v116, v117
	ds_read_b128 v[230:233], v12 offset:15424
	ds_read_b128 v[234:237], v12 offset:15440
	s_waitcnt lgkmcnt(5)
	v_fma_f32 v118, -v198, v112, v37
	v_fma_f32 v118, -v199, v113, v118
	v_fma_f32 v118, -v200, v114, v118
	v_fma_f32 v118, -v201, v115, v118
	s_waitcnt lgkmcnt(4)
	v_fma_f32 v118, -v202, v116, v118
	v_fma_f32 v118, -v203, v117, v118
	ds_read_b128 v[198:201], v12 offset:15696
	ds_read_b128 v[202:205], v12 offset:15712
	ds_read_b128 v[206:209], v12 offset:15728
	s_waitcnt lgkmcnt(6)
	v_fma_f32 v119, -v214, v112, v38
	v_fma_f32 v119, -v215, v113, v119
	v_fma_f32 v119, -v216, v114, v119
	v_fma_f32 v119, -v217, v115, v119
	s_waitcnt lgkmcnt(5)
	v_fma_f32 v119, -v218, v116, v119
	v_fma_f32 v119, -v219, v117, v119
	v_fma_f32 v119, -v220, v118, v119
	ds_read_b128 v[214:217], v12 offset:15968
	ds_read_b128 v[218:221], v12 offset:15984
	ds_read_b128 v[222:225], v12 offset:16000
	s_waitcnt lgkmcnt(7)
	v_fma_f32 v120, -v230, v112, v39
	v_fma_f32 v120, -v231, v113, v120
	v_fma_f32 v120, -v232, v114, v120
	v_fma_f32 v120, -v233, v115, v120
	s_waitcnt lgkmcnt(6)
	v_fma_f32 v120, -v234, v116, v120
	v_fma_f32 v120, -v235, v117, v120
	v_fma_f32 v120, -v236, v118, v120
	v_fma_f32 v120, -v237, v119, v120
	ds_read_b128 v[230:233], v12 offset:16240
	ds_read_b128 v[234:237], v12 offset:16256
	ds_read_b128 v[156:159], v12 offset:16272
	s_waitcnt lgkmcnt(8)
	v_fma_f32 v121, -v198, v112, v40
	v_fma_f32 v121, -v199, v113, v121
	v_fma_f32 v121, -v200, v114, v121
	v_fma_f32 v121, -v201, v115, v121
	s_waitcnt lgkmcnt(7)
	v_fma_f32 v121, -v202, v116, v121
	v_fma_f32 v121, -v203, v117, v121
	v_fma_f32 v121, -v204, v118, v121
	v_fma_f32 v121, -v205, v119, v121
	s_waitcnt lgkmcnt(6)
	v_fma_f32 v121, -v206, v120, v121
	ds_read_b128 v[198:201], v12 offset:16512
	ds_read_b128 v[202:205], v12 offset:16528
	ds_read_b128 v[206:209], v12 offset:16544
	s_waitcnt lgkmcnt(8)
	v_fma_f32 v122, -v214, v112, v41
	v_fma_f32 v122, -v215, v113, v122
	v_fma_f32 v122, -v216, v114, v122
	v_fma_f32 v122, -v217, v115, v122
	s_waitcnt lgkmcnt(7)
	v_fma_f32 v122, -v218, v116, v122
	v_fma_f32 v122, -v219, v117, v122
	v_fma_f32 v122, -v220, v118, v122
	v_fma_f32 v122, -v221, v119, v122
	s_waitcnt lgkmcnt(6)
	v_fma_f32 v122, -v222, v120, v122
	v_fma_f32 v122, -v223, v121, v122
	ds_read_b128 v[214:217], v12 offset:16784
	ds_read_b128 v[218:221], v12 offset:16800
	ds_read_b128 v[222:225], v12 offset:16816
	ds_read_b128 v[226:229], v12 offset:16832
	s_waitcnt lgkmcnt(9)
	v_fma_f32 v123, -v230, v112, v42
	v_fma_f32 v123, -v231, v113, v123
	v_fma_f32 v123, -v232, v114, v123
	v_fma_f32 v123, -v233, v115, v123
	s_waitcnt lgkmcnt(8)
	v_fma_f32 v123, -v234, v116, v123
	v_fma_f32 v123, -v235, v117, v123
	v_fma_f32 v123, -v236, v118, v123
	v_fma_f32 v123, -v237, v119, v123
	s_waitcnt lgkmcnt(7)
	v_fma_f32 v123, -v156, v120, v123
	v_fma_f32 v123, -v157, v121, v123
	v_fma_f32 v123, -v158, v122, v123
	ds_read_b128 v[230:233], v12 offset:17056
	ds_read_b128 v[234:237], v12 offset:17072
	ds_read_b128 v[156:159], v12 offset:17088
	ds_read_b128 v[164:167], v12 offset:17104
	s_waitcnt lgkmcnt(10)
	v_fma_f32 v56, -v198, v112, v43
	v_fma_f32 v56, -v199, v113, v56
	v_fma_f32 v56, -v200, v114, v56
	v_fma_f32 v56, -v201, v115, v56
	s_waitcnt lgkmcnt(9)
	v_fma_f32 v56, -v202, v116, v56
	v_fma_f32 v56, -v203, v117, v56
	v_fma_f32 v56, -v204, v118, v56
	v_fma_f32 v56, -v205, v119, v56
	s_waitcnt lgkmcnt(8)
	v_fma_f32 v56, -v206, v120, v56
	v_fma_f32 v56, -v207, v121, v56
	v_fma_f32 v56, -v208, v122, v56
	v_fma_f32 v56, -v209, v123, v56
	ds_read_b128 v[198:201], v12 offset:17328
	ds_read_b128 v[202:205], v12 offset:17344
	ds_read_b128 v[206:209], v12 offset:17360
	ds_read_b128 v[210:213], v12 offset:17376
	s_waitcnt lgkmcnt(11)
	v_fma_f32 v57, -v214, v112, v44
	v_fma_f32 v57, -v215, v113, v57
	v_fma_f32 v57, -v216, v114, v57
	v_fma_f32 v57, -v217, v115, v57
	s_waitcnt lgkmcnt(10)
	v_fma_f32 v57, -v218, v116, v57
	v_fma_f32 v57, -v219, v117, v57
	v_fma_f32 v57, -v220, v118, v57
	v_fma_f32 v57, -v221, v119, v57
	s_waitcnt lgkmcnt(9)
	v_fma_f32 v57, -v222, v120, v57
	v_fma_f32 v57, -v223, v121, v57
	v_fma_f32 v57, -v224, v122, v57
	v_fma_f32 v57, -v225, v123, v57
	s_waitcnt lgkmcnt(8)
	v_fma_f32 v57, -v226, v56, v57
	s_waitcnt lgkmcnt(7)
	v_fma_f32 v58, -v230, v112, v45
	v_fma_f32 v58, -v231, v113, v58
	v_fma_f32 v58, -v232, v114, v58
	v_fma_f32 v58, -v233, v115, v58
	s_waitcnt lgkmcnt(6)
	v_fma_f32 v58, -v234, v116, v58
	v_fma_f32 v58, -v235, v117, v58
	v_fma_f32 v58, -v236, v118, v58
	v_fma_f32 v58, -v237, v119, v58
	s_waitcnt lgkmcnt(5)
	v_fma_f32 v58, -v156, v120, v58
	v_fma_f32 v58, -v157, v121, v58
	v_fma_f32 v58, -v158, v122, v58
	v_fma_f32 v58, -v159, v123, v58
	s_waitcnt lgkmcnt(4)
	v_fma_f32 v58, -v164, v56, v58
	v_fma_f32 v58, -v165, v57, v58
	s_waitcnt lgkmcnt(3)
	v_fma_f32 v59, -v198, v112, v46
	v_fma_f32 v59, -v199, v113, v59
	v_fma_f32 v59, -v200, v114, v59
	v_fma_f32 v59, -v201, v115, v59
	s_waitcnt lgkmcnt(2)
	v_fma_f32 v59, -v202, v116, v59
	v_fma_f32 v59, -v203, v117, v59
	v_fma_f32 v59, -v204, v118, v59
	v_fma_f32 v59, -v205, v119, v59
	s_waitcnt lgkmcnt(1)
	v_fma_f32 v59, -v206, v120, v59
	v_fma_f32 v59, -v207, v121, v59
	v_fma_f32 v59, -v208, v122, v59
	v_fma_f32 v59, -v209, v123, v59
	s_waitcnt lgkmcnt(0)
	v_fma_f32 v59, -v210, v56, v59
	v_fma_f32 v59, -v211, v57, v59
	v_fma_f32 v59, -v212, v58, v59
	s_mov_b64 exec, 0xffff
	ds_write_b32 v9, v112 offset:12480
	ds_write_b32 v9, v113 offset:12740
	ds_write_b32 v9, v114 offset:13000
	ds_write_b32 v9, v115 offset:13260
	ds_write_b32 v9, v116 offset:13520
	ds_write_b32 v9, v117 offset:13780
	ds_write_b32 v9, v118 offset:14040
	ds_write_b32 v9, v119 offset:14300
	ds_write_b32 v9, v120 offset:14560
	ds_write_b32 v9, v121 offset:14820
	ds_write_b32 v9, v122 offset:15080
	ds_write_b32 v9, v123 offset:15340
	ds_write_b32 v9, v56 offset:15600
	ds_write_b32 v9, v57 offset:15860
	ds_write_b32 v9, v58 offset:16120
	s_waitcnt lgkmcnt(14)
	ds_write_b32 v9, v59 offset:16380
	s_mov_b64 exec, s[6:7]
	s_waitcnt lgkmcnt(0)
